# attention epilogue in O^T form: PV MFMA operands swapped, 1/denominator kept in registers, permlane32_swap half-wave exchange, row-per-lane dwordx4 gate loads and stores, no LDS transpose
# baseline (speedup 1.0000x reference)
.LBB0_687:
	s_add_i32 s10, s10, 1
	s_add_i32 s13, s13, 32
	s_add_i32 s12, s12, 1
	s_add_i32 s11, s11, 1
	v_mul_f32_e32 v82, v82, v0
	v_mul_f32_e32 v83, v83, v0
	v_mul_f32_e32 v84, v84, v0
	v_mul_f32_e32 v85, v85, v0
	v_mul_f32_e32 v86, v86, v0
	v_mul_f32_e32 v87, v87, v0
	v_mul_f32_e32 v88, v88, v0
	v_mul_f32_e32 v89, v89, v0
	s_nop 1
	v_permlane32_swap_b32_e32 v82, v86
	v_permlane32_swap_b32_e32 v83, v87
	v_permlane32_swap_b32_e32 v84, v88
	v_permlane32_swap_b32_e32 v85, v89
	s_waitcnt vmcnt(7)
	v_lshlrev_b32_e32 v2, 16, v98
	v_and_b32_e32 v3, 0xffff0000, v98
	v_lshlrev_b32_e32 v4, 16, v99
	v_and_b32_e32 v5, 0xffff0000, v99
	v_lshlrev_b32_e32 v6, 16, v100
	v_and_b32_e32 v7, 0xffff0000, v100
	v_lshlrev_b32_e32 v8, 16, v101
	v_and_b32_e32 v9, 0xffff0000, v101
	v_mul_f32_e32 v2, v82, v2
	v_mul_f32_e32 v3, v83, v3
	v_mul_f32_e32 v4, v84, v4
	v_mul_f32_e32 v5, v85, v5
	v_mul_f32_e32 v6, v86, v6
	v_mul_f32_e32 v7, v87, v7
	v_mul_f32_e32 v8, v88, v8
	v_mul_f32_e32 v9, v89, v9
	v_cvt_pk_bf16_f32 v10, v2, v3
	v_cvt_pk_bf16_f32 v11, v4, v5
	v_cvt_pk_bf16_f32 v12, v6, v7
	v_cvt_pk_bf16_f32 v13, v8, v9
	global_store_dwordx4 v26, v[10:13], s[50:51]
	v_mul_f32_e32 v90, v90, v0
	v_mul_f32_e32 v91, v91, v0
	v_mul_f32_e32 v92, v92, v0
	v_mul_f32_e32 v93, v93, v0
	v_mul_f32_e32 v94, v94, v0
	v_mul_f32_e32 v95, v95, v0
	v_mul_f32_e32 v96, v96, v0
	v_mul_f32_e32 v97, v97, v0
	s_nop 1
	v_permlane32_swap_b32_e32 v90, v94
	v_permlane32_swap_b32_e32 v91, v95
	v_permlane32_swap_b32_e32 v92, v96
	v_permlane32_swap_b32_e32 v93, v97
	s_waitcnt vmcnt(7)
	v_lshlrev_b32_e32 v2, 16, v102
	v_and_b32_e32 v3, 0xffff0000, v102
	v_lshlrev_b32_e32 v4, 16, v103
	v_and_b32_e32 v5, 0xffff0000, v103
	v_lshlrev_b32_e32 v6, 16, v104
	v_and_b32_e32 v7, 0xffff0000, v104
	v_lshlrev_b32_e32 v8, 16, v105
	v_and_b32_e32 v9, 0xffff0000, v105
	v_mul_f32_e32 v2, v90, v2
	v_mul_f32_e32 v3, v91, v3
	v_mul_f32_e32 v4, v92, v4
	v_mul_f32_e32 v5, v93, v5
	v_mul_f32_e32 v6, v94, v6
	v_mul_f32_e32 v7, v95, v7
	v_mul_f32_e32 v8, v96, v8
	v_mul_f32_e32 v9, v97, v9
	v_cvt_pk_bf16_f32 v14, v2, v3
	v_cvt_pk_bf16_f32 v15, v4, v5
	v_cvt_pk_bf16_f32 v16, v6, v7
	v_cvt_pk_bf16_f32 v17, v8, v9
	global_store_dwordx4 v26, v[14:17], s[50:51] offset:32
	v_mul_f32_e32 v66, v66, v0
	v_mul_f32_e32 v67, v67, v0
	v_mul_f32_e32 v68, v68, v0
	v_mul_f32_e32 v69, v69, v0
	v_mul_f32_e32 v70, v70, v0
	v_mul_f32_e32 v71, v71, v0
	v_mul_f32_e32 v72, v72, v0
	v_mul_f32_e32 v73, v73, v0
	s_nop 1
	v_permlane32_swap_b32_e32 v66, v70
	v_permlane32_swap_b32_e32 v67, v71
	v_permlane32_swap_b32_e32 v68, v72
	v_permlane32_swap_b32_e32 v69, v73
	s_waitcnt vmcnt(7)
	v_lshlrev_b32_e32 v2, 16, v106
	v_and_b32_e32 v3, 0xffff0000, v106
	v_lshlrev_b32_e32 v4, 16, v107
	v_and_b32_e32 v5, 0xffff0000, v107
	v_lshlrev_b32_e32 v6, 16, v108
	v_and_b32_e32 v7, 0xffff0000, v108
	v_lshlrev_b32_e32 v8, 16, v109
	v_and_b32_e32 v9, 0xffff0000, v109
	v_mul_f32_e32 v2, v66, v2
	v_mul_f32_e32 v3, v67, v3
	v_mul_f32_e32 v4, v68, v4
	v_mul_f32_e32 v5, v69, v5
	v_mul_f32_e32 v6, v70, v6
	v_mul_f32_e32 v7, v71, v7
	v_mul_f32_e32 v8, v72, v8
	v_mul_f32_e32 v9, v73, v9
	v_cvt_pk_bf16_f32 v10, v2, v3
	v_cvt_pk_bf16_f32 v11, v4, v5
	v_cvt_pk_bf16_f32 v12, v6, v7
	v_cvt_pk_bf16_f32 v13, v8, v9
	global_store_dwordx4 v26, v[10:13], s[50:51] offset:64
	v_mul_f32_e32 v74, v74, v0
	v_mul_f32_e32 v75, v75, v0
	v_mul_f32_e32 v76, v76, v0
	v_mul_f32_e32 v77, v77, v0
	v_mul_f32_e32 v78, v78, v0
	v_mul_f32_e32 v79, v79, v0
	v_mul_f32_e32 v80, v80, v0
	v_mul_f32_e32 v81, v81, v0
	s_nop 1
	v_permlane32_swap_b32_e32 v74, v78
	v_permlane32_swap_b32_e32 v75, v79
	v_permlane32_swap_b32_e32 v76, v80
	v_permlane32_swap_b32_e32 v77, v81
	s_waitcnt vmcnt(7)
	v_lshlrev_b32_e32 v2, 16, v110
	v_and_b32_e32 v3, 0xffff0000, v110
	v_lshlrev_b32_e32 v4, 16, v111
	v_and_b32_e32 v5, 0xffff0000, v111
	v_lshlrev_b32_e32 v6, 16, v112
	v_and_b32_e32 v7, 0xffff0000, v112
	v_lshlrev_b32_e32 v8, 16, v113
	v_and_b32_e32 v9, 0xffff0000, v113
	v_mul_f32_e32 v2, v74, v2
	v_mul_f32_e32 v3, v75, v3
	v_mul_f32_e32 v4, v76, v4
	v_mul_f32_e32 v5, v77, v5
	v_mul_f32_e32 v6, v78, v6
	v_mul_f32_e32 v7, v79, v7
	v_mul_f32_e32 v8, v80, v8
	v_mul_f32_e32 v9, v81, v9
	v_cvt_pk_bf16_f32 v14, v2, v3
	v_cvt_pk_bf16_f32 v15, v4, v5
	v_cvt_pk_bf16_f32 v16, v6, v7
	v_cvt_pk_bf16_f32 v17, v8, v9
	global_store_dwordx4 v26, v[14:17], s[50:51] offset:96
	v_mul_f32_e32 v50, v50, v0
	v_mul_f32_e32 v51, v51, v0
	v_mul_f32_e32 v52, v52, v0
	v_mul_f32_e32 v53, v53, v0
	v_mul_f32_e32 v54, v54, v0
	v_mul_f32_e32 v55, v55, v0
	v_mul_f32_e32 v56, v56, v0
	v_mul_f32_e32 v57, v57, v0
	s_nop 1
	v_permlane32_swap_b32_e32 v50, v54
	v_permlane32_swap_b32_e32 v51, v55
	v_permlane32_swap_b32_e32 v52, v56
	v_permlane32_swap_b32_e32 v53, v57
	s_waitcnt vmcnt(7)
	v_lshlrev_b32_e32 v2, 16, v114
	v_and_b32_e32 v3, 0xffff0000, v114
	v_lshlrev_b32_e32 v4, 16, v115
	v_and_b32_e32 v5, 0xffff0000, v115
	v_lshlrev_b32_e32 v6, 16, v116
	v_and_b32_e32 v7, 0xffff0000, v116
	v_lshlrev_b32_e32 v8, 16, v117
	v_and_b32_e32 v9, 0xffff0000, v117
	v_mul_f32_e32 v2, v50, v2
	v_mul_f32_e32 v3, v51, v3
	v_mul_f32_e32 v4, v52, v4
	v_mul_f32_e32 v5, v53, v5
	v_mul_f32_e32 v6, v54, v6
	v_mul_f32_e32 v7, v55, v7
	v_mul_f32_e32 v8, v56, v8
	v_mul_f32_e32 v9, v57, v9
	v_cvt_pk_bf16_f32 v10, v2, v3
	v_cvt_pk_bf16_f32 v11, v4, v5
	v_cvt_pk_bf16_f32 v12, v6, v7
	v_cvt_pk_bf16_f32 v13, v8, v9
	global_store_dwordx4 v26, v[10:13], s[50:51] offset:128
	v_mul_f32_e32 v58, v58, v0
	v_mul_f32_e32 v59, v59, v0
	v_mul_f32_e32 v60, v60, v0
	v_mul_f32_e32 v61, v61, v0
	v_mul_f32_e32 v62, v62, v0
	v_mul_f32_e32 v63, v63, v0
	v_mul_f32_e32 v64, v64, v0
	v_mul_f32_e32 v65, v65, v0
	s_nop 1
	v_permlane32_swap_b32_e32 v58, v62
	v_permlane32_swap_b32_e32 v59, v63
	v_permlane32_swap_b32_e32 v60, v64
	v_permlane32_swap_b32_e32 v61, v65
	s_waitcnt vmcnt(7)
	v_lshlrev_b32_e32 v2, 16, v118
	v_and_b32_e32 v3, 0xffff0000, v118
	v_lshlrev_b32_e32 v4, 16, v119
	v_and_b32_e32 v5, 0xffff0000, v119
	v_lshlrev_b32_e32 v6, 16, v120
	v_and_b32_e32 v7, 0xffff0000, v120
	v_lshlrev_b32_e32 v8, 16, v121
	v_and_b32_e32 v9, 0xffff0000, v121
	v_mul_f32_e32 v2, v58, v2
	v_mul_f32_e32 v3, v59, v3
	v_mul_f32_e32 v4, v60, v4
	v_mul_f32_e32 v5, v61, v5
	v_mul_f32_e32 v6, v62, v6
	v_mul_f32_e32 v7, v63, v7
	v_mul_f32_e32 v8, v64, v8
	v_mul_f32_e32 v9, v65, v9
	v_cvt_pk_bf16_f32 v14, v2, v3
	v_cvt_pk_bf16_f32 v15, v4, v5
	v_cvt_pk_bf16_f32 v16, v6, v7
	v_cvt_pk_bf16_f32 v17, v8, v9
	global_store_dwordx4 v26, v[14:17], s[50:51] offset:160
	v_mul_f32_e32 v34, v34, v0
	v_mul_f32_e32 v35, v35, v0
	v_mul_f32_e32 v36, v36, v0
	v_mul_f32_e32 v37, v37, v0
	v_mul_f32_e32 v38, v38, v0
	v_mul_f32_e32 v39, v39, v0
	v_mul_f32_e32 v40, v40, v0
	v_mul_f32_e32 v41, v41, v0
	s_nop 1
	v_permlane32_swap_b32_e32 v34, v38
	v_permlane32_swap_b32_e32 v35, v39
	v_permlane32_swap_b32_e32 v36, v40
	v_permlane32_swap_b32_e32 v37, v41
	s_waitcnt vmcnt(7)
	v_lshlrev_b32_e32 v2, 16, v122
	v_and_b32_e32 v3, 0xffff0000, v122
	v_lshlrev_b32_e32 v4, 16, v123
	v_and_b32_e32 v5, 0xffff0000, v123
	v_lshlrev_b32_e32 v6, 16, v124
	v_and_b32_e32 v7, 0xffff0000, v124
	v_lshlrev_b32_e32 v8, 16, v125
	v_and_b32_e32 v9, 0xffff0000, v125
	v_mul_f32_e32 v2, v34, v2
	v_mul_f32_e32 v3, v35, v3
	v_mul_f32_e32 v4, v36, v4
	v_mul_f32_e32 v5, v37, v5
	v_mul_f32_e32 v6, v38, v6
	v_mul_f32_e32 v7, v39, v7
	v_mul_f32_e32 v8, v40, v8
	v_mul_f32_e32 v9, v41, v9
	v_cvt_pk_bf16_f32 v10, v2, v3
	v_cvt_pk_bf16_f32 v11, v4, v5
	v_cvt_pk_bf16_f32 v12, v6, v7
	v_cvt_pk_bf16_f32 v13, v8, v9
	global_store_dwordx4 v26, v[10:13], s[50:51] offset:192
	v_mul_f32_e32 v42, v42, v0
	v_mul_f32_e32 v43, v43, v0
	v_mul_f32_e32 v44, v44, v0
	v_mul_f32_e32 v45, v45, v0
	v_mul_f32_e32 v46, v46, v0
	v_mul_f32_e32 v47, v47, v0
	v_mul_f32_e32 v48, v48, v0
	v_mul_f32_e32 v49, v49, v0
	s_nop 1
	v_permlane32_swap_b32_e32 v42, v46
	v_permlane32_swap_b32_e32 v43, v47
	v_permlane32_swap_b32_e32 v44, v48
	v_permlane32_swap_b32_e32 v45, v49
	s_waitcnt vmcnt(7)
	v_lshlrev_b32_e32 v2, 16, v126
	v_and_b32_e32 v3, 0xffff0000, v126
	v_lshlrev_b32_e32 v4, 16, v127
	v_and_b32_e32 v5, 0xffff0000, v127
	v_lshlrev_b32_e32 v6, 16, v128
	v_and_b32_e32 v7, 0xffff0000, v128
	v_lshlrev_b32_e32 v8, 16, v129
	v_and_b32_e32 v9, 0xffff0000, v129
	v_mul_f32_e32 v2, v42, v2
	v_mul_f32_e32 v3, v43, v3
	v_mul_f32_e32 v4, v44, v4
	v_mul_f32_e32 v5, v45, v5
	v_mul_f32_e32 v6, v46, v6
	v_mul_f32_e32 v7, v47, v7
	v_mul_f32_e32 v8, v48, v8
	v_mul_f32_e32 v9, v49, v9
	v_cvt_pk_bf16_f32 v14, v2, v3
	v_cvt_pk_bf16_f32 v15, v4, v5
	v_cvt_pk_bf16_f32 v16, v6, v7
	v_cvt_pk_bf16_f32 v17, v8, v9
	global_store_dwordx4 v26, v[14:17], s[50:51] offset:224
	v_readlane_b32 s8, v255, 11
	s_cmp_eq_u32 s10, s8
	s_cselect_b64 s[8:9], -1, 0
	v_mov_b32_e32 v159, v33

.LBB0_693:
	s_add_i32 s17, s14, s16
	s_bitcmp1_b32 s16, 0
	s_cselect_b32 s8, 0x8800, 0
	s_add_i32 s23, s8, 0
	v_add_u32_e32 v0, s23, v172
	ds_read_b128 v[0:3], v0
	v_add_u32_e32 v209, s23, v174
	ds_read_b128 v[234:237], v209
	v_add_u32_e32 v209, s23, v175
	s_and_b32 s8, s17, -5
	s_cmp_eq_u32 s8, 0
	s_waitcnt lgkmcnt(1)
	v_mfma_f32_32x32x16_bf16 v[16:31], v[0:3], v[122:125], 0
	v_add_u32_e32 v0, s23, v173
	ds_read_b128 v[0:3], v0
	s_waitcnt lgkmcnt(1)
	v_mfma_f32_32x32x16_bf16 v[16:31], v[234:237], v[126:129], v[16:31]
	ds_read_b128 v[234:237], v209
	v_add_u32_e32 v209, s23, v176
	s_waitcnt lgkmcnt(1)
	v_mfma_f32_32x32x16_bf16 v[0:15], v[0:3], v[122:125], 0
	s_waitcnt lgkmcnt(0)
	v_mfma_f32_32x32x16_bf16 v[0:15], v[234:237], v[126:129], v[0:15]
	ds_read_b128 v[234:237], v209
	v_add_u32_e32 v209, s23, v177
	s_waitcnt lgkmcnt(0)
	v_mfma_f32_32x32x16_bf16 v[16:31], v[234:237], v[98:101], v[16:31]
	ds_read_b128 v[234:237], v209
	v_add_u32_e32 v209, s23, v185
	s_waitcnt lgkmcnt(0)
	v_mfma_f32_32x32x16_bf16 v[0:15], v[234:237], v[98:101], v[0:15]
	ds_read_b128 v[234:237], v209
	v_add_u32_e32 v209, s23, v190
	s_waitcnt lgkmcnt(0)
	v_mfma_f32_32x32x16_bf16 v[16:31], v[234:237], v[102:105], v[16:31]
	ds_read_b128 v[234:237], v209
	v_add_u32_e32 v209, s23, v191
	s_waitcnt lgkmcnt(0)
	v_mfma_f32_32x32x16_bf16 v[0:15], v[234:237], v[102:105], v[0:15]
	ds_read_b128 v[234:237], v209
	v_add_u32_e32 v209, s23, v192
	s_waitcnt lgkmcnt(0)
	v_mfma_f32_32x32x16_bf16 v[16:31], v[234:237], v[106:109], v[16:31]
	ds_read_b128 v[234:237], v209
	v_add_u32_e32 v209, s23, v193
	s_waitcnt lgkmcnt(0)
	v_mfma_f32_32x32x16_bf16 v[0:15], v[234:237], v[106:109], v[0:15]
	ds_read_b128 v[234:237], v209
	v_add_u32_e32 v209, s23, v194
	s_waitcnt lgkmcnt(0)
	v_mfma_f32_32x32x16_bf16 v[16:31], v[234:237], v[110:113], v[16:31]
	ds_read_b128 v[234:237], v209
	v_add_u32_e32 v209, s23, v195
	s_waitcnt lgkmcnt(0)
	v_mfma_f32_32x32x16_bf16 v[0:15], v[234:237], v[110:113], v[0:15]
	ds_read_b128 v[234:237], v209
	v_add_u32_e32 v209, s23, v196
	s_waitcnt lgkmcnt(0)
	v_mfma_f32_32x32x16_bf16 v[16:31], v[234:237], v[114:117], v[16:31]
	ds_read_b128 v[234:237], v209
	v_add_u32_e32 v209, s23, v197
	s_waitcnt lgkmcnt(0)
	v_mfma_f32_32x32x16_bf16 v[0:15], v[234:237], v[114:117], v[0:15]
	ds_read_b128 v[234:237], v209
	v_add_u32_e32 v209, s23, v198
	s_waitcnt lgkmcnt(0)
	v_mfma_f32_32x32x16_bf16 v[16:31], v[234:237], v[118:121], v[16:31]
	ds_read_b128 v[234:237], v209
	s_waitcnt lgkmcnt(0)
	v_mfma_f32_32x32x16_bf16 v[0:15], v[234:237], v[118:121], v[0:15]
	s_cselect_b32 s9, 1, 0
	s_cmp_lt_i32 s17, s15
	s_cbranch_scc1 .Lattn_nogate
	v_add_u32_e32 v130, v159, v146
	v_mul_lo_u32 v130, v130, s97
	v_lshl_add_u32 v130, v160, 1, v130
	v_lshl_add_u32 v130, v168, 2, v130
	v_add_u32_e32 v130, 0x1400, v130
	global_load_dwordx4 v[98:101], v130, s[0:1]
	global_load_dwordx4 v[102:105], v130, s[0:1] offset:32
	global_load_dwordx4 v[106:109], v130, s[0:1] offset:64
	global_load_dwordx4 v[110:113], v130, s[0:1] offset:96
	global_load_dwordx4 v[114:117], v130, s[0:1] offset:128
	global_load_dwordx4 v[118:121], v130, s[0:1] offset:160
	global_load_dwordx4 v[122:125], v130, s[0:1] offset:192
	global_load_dwordx4 v[126:129], v130, s[0:1] offset:224

.LBB0_696:
	v_cvt_pk_bf16_f32 v0, v0, v1
	v_cvt_pk_bf16_f32 v1, v2, v3
	v_cvt_pk_bf16_f32 v2, v4, v5
	v_cvt_pk_bf16_f32 v3, v6, v7
	v_cvt_pk_bf16_f32 v4, v8, v9
	v_cvt_pk_bf16_f32 v5, v10, v11
	v_cvt_pk_bf16_f32 v6, v12, v13
	v_cvt_pk_bf16_f32 v7, v14, v15
	v_cvt_pk_bf16_f32 v8, v16, v17
	v_cvt_pk_bf16_f32 v9, v18, v19
	v_cvt_pk_bf16_f32 v10, v20, v21
	v_cvt_pk_bf16_f32 v11, v22, v23
	v_cvt_pk_bf16_f32 v12, v24, v25
	v_cvt_pk_bf16_f32 v13, v26, v27
	ds_write2_b64 v204, v[0:1], v[2:3] offset1:2
	ds_write2_b64 v204, v[4:5], v[6:7] offset0:4 offset1:6
	ds_write2_b64 v204, v[8:9], v[10:11] offset0:8 offset1:10
	v_cvt_pk_bf16_f32 v0, v28, v29
	v_cvt_pk_bf16_f32 v1, v30, v31
	ds_write2_b64 v204, v[12:13], v[0:1] offset0:12 offset1:14
	s_addk_i32 s23, 0x4400
	v_add_u32_e32 v242, s23, v199
	ds_read_b128 v[0:3], v205
	ds_read_b64_tr_b16 v[16:17], v242 offset:0
	ds_read_b64_tr_b16 v[18:19], v242 offset:1088
	ds_read_b64_tr_b16 v[12:13], v242 offset:64
	ds_read_b64_tr_b16 v[14:15], v242 offset:1152
	ds_read_b64_tr_b16 v[8:9], v242 offset:128
	ds_read_b64_tr_b16 v[10:11], v242 offset:1216
	ds_read_b64_tr_b16 v[4:5], v242 offset:192
	ds_read_b64_tr_b16 v[6:7], v242 offset:1280
	v_add_u32_e32 v243, s23, v200
	ds_read_b128 v[20:23], v205 offset:32
	ds_read_b64_tr_b16 v[24:25], v243 offset:0
	ds_read_b64_tr_b16 v[26:27], v243 offset:1088
	ds_read_b64_tr_b16 v[28:29], v243 offset:64
	ds_read_b64_tr_b16 v[30:31], v243 offset:1152
	ds_read_b64_tr_b16 v[234:235], v243 offset:128
	ds_read_b64_tr_b16 v[236:237], v243 offset:1216
	ds_read_b64_tr_b16 v[238:239], v243 offset:192
	ds_read_b64_tr_b16 v[240:241], v243 offset:1280
	s_mov_b64 s[8:9], -1
	s_waitcnt lgkmcnt(9)
	v_mfma_f32_32x32x16_bf16 v[82:97], v[16:19], v[0:3], v[82:97]
	v_mfma_f32_32x32x16_bf16 v[66:81], v[12:15], v[0:3], v[66:81]
	v_mfma_f32_32x32x16_bf16 v[50:65], v[8:11], v[0:3], v[50:65]
	v_mfma_f32_32x32x16_bf16 v[34:49], v[4:7], v[0:3], v[34:49]
	v_add_u32_e32 v242, s23, v201
	ds_read_b128 v[0:3], v205 offset:64
	ds_read_b64_tr_b16 v[16:17], v242 offset:0
	ds_read_b64_tr_b16 v[18:19], v242 offset:1088
	ds_read_b64_tr_b16 v[12:13], v242 offset:64
	ds_read_b64_tr_b16 v[14:15], v242 offset:1152
	ds_read_b64_tr_b16 v[8:9], v242 offset:128
	ds_read_b64_tr_b16 v[10:11], v242 offset:1216
	ds_read_b64_tr_b16 v[4:5], v242 offset:192
	ds_read_b64_tr_b16 v[6:7], v242 offset:1280
	s_waitcnt lgkmcnt(9)
	v_mfma_f32_32x32x16_bf16 v[82:97], v[24:27], v[20:23], v[82:97]
	v_mfma_f32_32x32x16_bf16 v[66:81], v[28:31], v[20:23], v[66:81]
	v_mfma_f32_32x32x16_bf16 v[50:65], v[234:237], v[20:23], v[50:65]
	v_mfma_f32_32x32x16_bf16 v[34:49], v[238:241], v[20:23], v[34:49]
	v_add_u32_e32 v243, s23, v202
	ds_read_b128 v[20:23], v205 offset:96
	ds_read_b64_tr_b16 v[24:25], v243 offset:0
	ds_read_b64_tr_b16 v[26:27], v243 offset:1088
	ds_read_b64_tr_b16 v[28:29], v243 offset:64
	ds_read_b64_tr_b16 v[30:31], v243 offset:1152
	ds_read_b64_tr_b16 v[234:235], v243 offset:128
	ds_read_b64_tr_b16 v[236:237], v243 offset:1216
	ds_read_b64_tr_b16 v[238:239], v243 offset:192
	ds_read_b64_tr_b16 v[240:241], v243 offset:1280
	s_waitcnt lgkmcnt(9)
	v_mfma_f32_32x32x16_bf16 v[82:97], v[16:19], v[0:3], v[82:97]
	v_mfma_f32_32x32x16_bf16 v[66:81], v[12:15], v[0:3], v[66:81]
	v_mfma_f32_32x32x16_bf16 v[50:65], v[8:11], v[0:3], v[50:65]
	v_mfma_f32_32x32x16_bf16 v[34:49], v[4:7], v[0:3], v[34:49]
	s_cmp_lt_i32 s17, s15
	s_cbranch_scc0 .Lattn_nostage
	s_add_i32 s23, s16, 1
	s_bitcmp1_b32 s23, 0
	s_cselect_b32 s23, 0x8800, 0
	v_add_u32_e32 v244, s23, v171
	s_waitcnt vmcnt(3)
	ds_write_b128 v244, v[130:133]
	s_waitcnt vmcnt(2)
	ds_write_b128 v244, v[134:137] offset:17408
	s_waitcnt vmcnt(1)
	ds_write_b128 v244, v[138:141] offset:8704
	s_waitcnt vmcnt(0)
	ds_write_b128 v244, v[142:145] offset:26112
	s_add_i32 s23, s17, 1
	s_cmp_ge_i32 s23, s15
	s_cbranch_scc1 .Lattn_noload
	v_add_co_u32_e32 v244, vcc, 0xfffa8000, v162
	s_nop 1
	v_addc_co_u32_e32 v245, vcc, -1, v163, vcc
	global_load_dwordx4 v[130:133], v[244:245], off offset:-512
	global_load_dwordx4 v[134:137], v[244:245], off
	global_load_dwordx4 v[138:141], v[162:163], off offset:-512
	global_load_dwordx4 v[142:145], v[162:163], off

.Lattn_stage_done:
	v_mfma_f32_32x32x16_bf16 v[82:97], v[24:27], v[20:23], v[82:97]
	v_mfma_f32_32x32x16_bf16 v[66:81], v[28:31], v[20:23], v[66:81]
	v_mfma_f32_32x32x16_bf16 v[50:65], v[234:237], v[20:23], v[50:65]
	v_mfma_f32_32x32x16_bf16 v[34:49], v[238:241], v[20:23], v[34:49]
	s_cmp_lt_i32 s17, s15
	s_cbranch_scc1 .LBB0_698
	s_add_i32 s23, s16, 1
	s_mov_b64 s[8:9], 0

.LBB0_705:
	ds_bpermute_b32 v0, v147, v209
	v_add_u32_e32 v26, v159, v146
	v_lshlrev_b32_e32 v26, 12, v26
	v_lshl_add_u32 v26, v160, 1, v26
	v_lshl_add_u32 v26, v168, 2, v26
	v_add_u32_e32 v26, 0x55d0400, v26
	v_sub_f32_e32 v1, v157, v206
	v_cmp_gt_f32_e32 vcc, s20, v1
	s_waitcnt lgkmcnt(0)
	v_add_f32_e32 v0, v209, v0
	v_cndmask_b32_e32 v2, 0, v228, vcc
	v_add_f32_e32 v1, v1, v2
	v_exp_f32_e32 v1, v1
	v_cndmask_b32_e32 v2, 0, v223, vcc
	v_ldexp_f32 v1, v1, v2
	v_add_f32_e32 v0, v1, v0
	v_div_scale_f32 v1, s[14:15], v0, v0, 1.0
	v_rcp_f32_e32 v2, v1
	v_div_scale_f32 v3, vcc, 1.0, v0, 1.0
	v_fma_f32 v4, -v1, v2, 1.0
	v_fmac_f32_e32 v2, v4, v2
	v_mul_f32_e32 v4, v3, v2
	v_fma_f32 v5, -v1, v4, v3
	v_fmac_f32_e32 v4, v5, v2
	v_fma_f32 v1, -v1, v4, v3
	v_div_fmas_f32 v1, v1, v2, v4
	v_div_fixup_f32 v0, v1, v0, 1.0
	s_branch .LBB0_687
